# DSA select compaction loop: next key block's score read issued during the current block's processing
# baseline (speedup 1.0000x reference)
.LBB0_234:
	s_or_b64 exec, exec, s[34:35]
	s_lshl_b32 s78, s87, 9
	v_cndmask_b32_e64 v3, 0, 1, s[28:29]
	s_add_i32 s78, s78, 0x11000
	v_cmp_ne_u32_e32 vcc, 0, v3
	s_ff1_i32_b64 s28, vcc
	s_cmp_lg_u64 vcc, 0
	s_cselect_b32 s28, s28, 63
	v_or_b32_e32 v4, s28, v15
	v_or_b32_e32 v3, v10, v174
	v_lshlrev_b32_e32 v4, 2, v4
	ds_bpermute_b32 v3, v4, v3
	ds_bpermute_b32 v4, v4, v2
	s_waitcnt lgkmcnt(0)
	s_mov_b32 s79, 0
	v_mov_b32_e32 v5, v167
	s_waitcnt lgkmcnt(1)
	v_lshl_or_b32 v2, v13, 8, v3
	s_waitcnt lgkmcnt(0)
	v_sub_u32_e32 v3, v9, v4
	v_sub_u32_e32 v4, s95, v3
	v_lshl_add_u32 v4, v4, 1, s78
	s_mov_b32 s87, 0
	ds_read_u16 v207, v8
	s_branch .LBB0_236

.LBB0_236:
	s_waitcnt lgkmcnt(0)
	v_mov_b32_e32 v9, v207
	ds_read_u16 v207, v8 offset:128
	v_cmp_ge_u32_e32 vcc, s50, v5
	v_cmp_lt_u32_sdwa s[28:29], v2, v9 src0_sel:DWORD src1_sel:WORD_0
	s_and_b64 s[90:91], vcc, s[28:29]
	v_cmp_eq_u32_sdwa s[28:29], v2, v9 src0_sel:DWORD src1_sel:WORD_0
	s_and_b64 s[42:43], vcc, s[28:29]
	v_cndmask_b32_e64 v9, 0, 1, s[90:91]
	v_cmp_ne_u32_e32 vcc, 0, v9
	v_cndmask_b32_e64 v9, 0, 1, s[42:43]
	v_cmp_ne_u32_e64 s[28:29], 0, v9
	s_and_saveexec_b64 s[34:35], s[90:91]
	s_cbranch_execz .LBB0_238
	v_and_b32_e32 v10, vcc_lo, v146
	s_lshl_b32 s90, s79, 1
	v_and_b32_e32 v9, vcc_hi, v1
	v_bcnt_u32_b32 v10, v10, 0
	s_add_i32 s90, s78, s90
	v_bcnt_u32_b32 v9, v9, v10
	v_lshl_add_u32 v9, v9, 1, s90
	ds_write_b16 v9, v5
